# v73 + non-temporal hint on the read-once residual loads of the P9 and P13 fused epilogues
# baseline (speedup 1.0000x reference)
.LBB0_905:
	s_lshl_b32 s1, s0, 8
	v_add_u32_e32 v160, s1, v162
	v_lshl_add_u32 v144, s14, 8, v164
	v_ashrrev_i32_e32 v161, 31, v160
	v_ashrrev_i32_e32 v145, 31, v144
	v_readlane_b32 s36, v235, 13
	v_readlane_b32 s37, v235, 14
	s_nop 2
	v_lshl_add_u64 v[222:223], v[144:145], 2, s[36:37]
	global_load_dwordx4 v[206:209], v[222:223], off nt
	global_load_dwordx4 v[210:213], v[222:223], off offset:64 nt
	global_load_dwordx4 v[214:217], v[222:223], off offset:512 nt
	global_load_dwordx4 v[218:221], v[222:223], off offset:576 nt
	v_lshlrev_b64 v[128:129], 11, v[160:161]
	v_readlane_b32 s56, v235, 28
	v_lshl_add_u64 v[128:129], v[128:129], 0, v[144:145]
	v_readlane_b32 s57, v235, 29
	v_lshlrev_b64 v[146:147], 2, v[128:129]
	s_mov_b64 s[16:17], s[56:57]
	v_lshl_add_u64 v[148:149], s[16:17], 0, v[146:147]
	global_load_dwordx4 v[128:131], v[148:149], off nt
	v_lshl_add_u64 v[146:147], s[72:73], 0, v[146:147]
	v_or_b32_e32 v158, 16, v160
	v_ashrrev_i32_e32 v159, 31, v158
	v_or_b32_e32 v156, 32, v160
	v_ashrrev_i32_e32 v157, 31, v156
	v_or_b32_e32 v154, 48, v160
	v_ashrrev_i32_e32 v155, 31, v154
	v_add_u32_e32 v152, 0x80, v160
	v_ashrrev_i32_e32 v153, 31, v152
	v_readlane_b32 s58, v235, 30
	v_readlane_b32 s59, v235, 31
	v_readlane_b32 s60, v235, 32
	v_readlane_b32 s61, v235, 33
	v_readlane_b32 s62, v235, 34
	v_readlane_b32 s63, v235, 35
	v_readlane_b32 s64, v235, 36
	v_readlane_b32 s65, v235, 37
	v_readlane_b32 s66, v235, 38
	v_readlane_b32 s67, v235, 39
	v_readlane_b32 s68, v235, 40
	v_readlane_b32 s69, v235, 41
	v_readlane_b32 s70, v235, 42
	v_readlane_b32 s71, v235, 43
	s_waitcnt vmcnt(0)
	v_pk_add_f32 v[130:131], v[126:127], v[130:131]
	v_pk_add_f32 v[128:129], v[124:125], v[128:129]
	global_store_dwordx4 v[146:147], v[128:131], off
	global_load_dwordx4 v[124:127], v[148:149], off offset:64 nt
	s_waitcnt vmcnt(0)
	v_pk_add_f32 v[122:123], v[122:123], v[126:127]
	v_pk_add_f32 v[120:121], v[120:121], v[124:125]
	global_store_dwordx4 v[146:147], v[120:123], off offset:64
	global_load_dwordx4 v[124:127], v[148:149], off offset:512 nt
	s_waitcnt vmcnt(0)
	v_pk_add_f32 v[118:119], v[118:119], v[126:127]
	v_pk_add_f32 v[116:117], v[116:117], v[124:125]
	global_store_dwordx4 v[146:147], v[116:119], off offset:512
	global_load_dwordx4 v[124:127], v[148:149], off offset:576 nt
	v_lshlrev_b64 v[148:149], 11, v[158:159]
	v_lshl_add_u64 v[148:149], v[148:149], 0, v[144:145]
	v_lshlrev_b64 v[148:149], 2, v[148:149]
	v_lshl_add_u64 v[150:151], s[16:17], 0, v[148:149]
	s_waitcnt vmcnt(0)
	v_pk_add_f32 v[126:127], v[106:107], v[126:127]
	v_pk_add_f32 v[124:125], v[104:105], v[124:125]
	global_store_dwordx4 v[146:147], v[124:127], off offset:576
	global_load_dwordx4 v[104:107], v[150:151], off nt
	v_lshl_add_u64 v[146:147], s[72:73], 0, v[148:149]
	v_lshlrev_b64 v[148:149], 11, v[156:157]
	v_lshl_add_u64 v[148:149], v[148:149], 0, v[144:145]
	v_lshlrev_b64 v[148:149], 2, v[148:149]
	s_waitcnt vmcnt(0)
	v_pk_add_f32 v[114:115], v[114:115], v[106:107]
	v_pk_add_f32 v[112:113], v[112:113], v[104:105]
	global_store_dwordx4 v[146:147], v[112:115], off
	global_load_dwordx4 v[104:107], v[150:151], off offset:64 nt
	s_waitcnt vmcnt(0)
	v_pk_add_f32 v[106:107], v[110:111], v[106:107]
	v_pk_add_f32 v[104:105], v[108:109], v[104:105]
	global_store_dwordx4 v[146:147], v[104:107], off offset:64
	global_load_dwordx4 v[108:111], v[150:151], off offset:512 nt
	s_waitcnt vmcnt(0)
	v_pk_add_f32 v[102:103], v[102:103], v[110:111]
	v_pk_add_f32 v[100:101], v[100:101], v[108:109]
	global_store_dwordx4 v[146:147], v[100:103], off offset:512
	global_load_dwordx4 v[108:111], v[150:151], off offset:576 nt
	v_lshl_add_u64 v[150:151], s[16:17], 0, v[148:149]
	s_waitcnt vmcnt(0)
	v_pk_add_f32 v[110:111], v[90:91], v[110:111]
	v_pk_add_f32 v[108:109], v[88:89], v[108:109]
	global_store_dwordx4 v[146:147], v[108:111], off offset:576
	global_load_dwordx4 v[88:91], v[150:151], off nt
	v_lshl_add_u64 v[146:147], s[72:73], 0, v[148:149]
	v_lshlrev_b64 v[148:149], 11, v[154:155]
	v_lshl_add_u64 v[148:149], v[148:149], 0, v[144:145]
	v_lshlrev_b64 v[148:149], 2, v[148:149]
	s_waitcnt vmcnt(0)
	v_pk_add_f32 v[98:99], v[98:99], v[90:91]
	v_pk_add_f32 v[96:97], v[96:97], v[88:89]
	global_store_dwordx4 v[146:147], v[96:99], off
	global_load_dwordx4 v[88:91], v[150:151], off offset:64 nt
	s_waitcnt vmcnt(0)
	v_pk_add_f32 v[90:91], v[94:95], v[90:91]
	v_pk_add_f32 v[88:89], v[92:93], v[88:89]
	global_store_dwordx4 v[146:147], v[88:91], off offset:64
	global_load_dwordx4 v[92:95], v[150:151], off offset:512 nt
	s_waitcnt vmcnt(0)
	v_pk_add_f32 v[86:87], v[86:87], v[94:95]
	v_pk_add_f32 v[84:85], v[84:85], v[92:93]
	global_store_dwordx4 v[146:147], v[84:87], off offset:512
	global_load_dwordx4 v[92:95], v[150:151], off offset:576 nt
	v_lshl_add_u64 v[150:151], s[16:17], 0, v[148:149]
	s_waitcnt vmcnt(0)
	v_pk_add_f32 v[94:95], v[74:75], v[94:95]
	v_pk_add_f32 v[92:93], v[72:73], v[92:93]
	global_store_dwordx4 v[146:147], v[92:95], off offset:576
	global_load_dwordx4 v[72:75], v[150:151], off nt
	v_lshl_add_u64 v[146:147], s[72:73], 0, v[148:149]
	v_lshlrev_b64 v[148:149], 11, v[152:153]
	v_lshl_add_u64 v[148:149], v[148:149], 0, v[144:145]
	v_lshlrev_b64 v[148:149], 2, v[148:149]
	s_waitcnt vmcnt(0)
	v_pk_add_f32 v[82:83], v[82:83], v[74:75]
	v_pk_add_f32 v[80:81], v[80:81], v[72:73]
	global_store_dwordx4 v[146:147], v[80:83], off
	global_load_dwordx4 v[72:75], v[150:151], off offset:64 nt
	s_waitcnt vmcnt(0)
	v_pk_add_f32 v[74:75], v[78:79], v[74:75]
	v_pk_add_f32 v[72:73], v[76:77], v[72:73]
	global_store_dwordx4 v[146:147], v[72:75], off offset:64
	global_load_dwordx4 v[76:79], v[150:151], off offset:512 nt
	s_waitcnt vmcnt(0)
	v_pk_add_f32 v[70:71], v[70:71], v[78:79]
	v_pk_add_f32 v[68:69], v[68:69], v[76:77]
	global_store_dwordx4 v[146:147], v[68:71], off offset:512
	global_load_dwordx4 v[76:79], v[150:151], off offset:576 nt
	v_lshl_add_u64 v[150:151], s[16:17], 0, v[148:149]
	s_waitcnt vmcnt(0)
	v_pk_add_f32 v[78:79], v[66:67], v[78:79]
	v_pk_add_f32 v[76:77], v[64:65], v[76:77]
	global_store_dwordx4 v[146:147], v[76:79], off offset:576
	global_load_dwordx4 v[64:67], v[150:151], off nt
	v_lshl_add_u64 v[146:147], s[72:73], 0, v[148:149]
	s_waitcnt vmcnt(0)
	v_pk_add_f32 v[66:67], v[62:63], v[66:67]
	v_pk_add_f32 v[64:65], v[60:61], v[64:65]
	global_store_dwordx4 v[146:147], v[64:67], off
	global_load_dwordx4 v[60:63], v[150:151], off offset:64 nt
	s_waitcnt vmcnt(0)
	v_pk_add_f32 v[58:59], v[58:59], v[62:63]
	v_pk_add_f32 v[56:57], v[56:57], v[60:61]
	global_store_dwordx4 v[146:147], v[56:59], off offset:64
	global_load_dwordx4 v[60:63], v[150:151], off offset:512 nt
	s_waitcnt vmcnt(0)
	v_pk_add_f32 v[54:55], v[54:55], v[62:63]
	v_pk_add_f32 v[52:53], v[52:53], v[60:61]
	global_store_dwordx4 v[146:147], v[52:55], off offset:512
	global_load_dwordx4 v[60:63], v[150:151], off offset:576 nt
	v_add_u32_e32 v150, 0x90, v160
	v_ashrrev_i32_e32 v151, 31, v150
	v_lshlrev_b64 v[148:149], 11, v[150:151]
	v_lshl_add_u64 v[148:149], v[148:149], 0, v[144:145]
	v_lshlrev_b64 v[148:149], 2, v[148:149]
	v_lshl_add_u64 v[174:175], s[16:17], 0, v[148:149]
	s_waitcnt vmcnt(0)
	v_pk_add_f32 v[62:63], v[42:43], v[62:63]
	v_pk_add_f32 v[60:61], v[40:41], v[60:61]
	global_store_dwordx4 v[146:147], v[60:63], off offset:576
	global_load_dwordx4 v[40:43], v[174:175], off nt
	v_lshl_add_u64 v[146:147], s[72:73], 0, v[148:149]
	v_add_u32_e32 v148, 0xa0, v160
	v_ashrrev_i32_e32 v149, 31, v148
	s_waitcnt vmcnt(0)
	v_pk_add_f32 v[50:51], v[50:51], v[42:43]
	v_pk_add_f32 v[48:49], v[48:49], v[40:41]
	global_store_dwordx4 v[146:147], v[48:51], off
	global_load_dwordx4 v[40:43], v[174:175], off offset:64 nt
	s_waitcnt vmcnt(0)
	v_pk_add_f32 v[42:43], v[46:47], v[42:43]
	v_pk_add_f32 v[40:41], v[44:45], v[40:41]
	global_store_dwordx4 v[146:147], v[40:43], off offset:64
	global_load_dwordx4 v[44:47], v[174:175], off offset:512 nt
	s_waitcnt vmcnt(0)
	v_pk_add_f32 v[38:39], v[38:39], v[46:47]
	v_pk_add_f32 v[36:37], v[36:37], v[44:45]
	global_store_dwordx4 v[146:147], v[36:39], off offset:512
	global_load_dwordx4 v[44:47], v[174:175], off offset:576 nt
	v_lshlrev_b64 v[174:175], 11, v[148:149]
	v_lshl_add_u64 v[174:175], v[174:175], 0, v[144:145]
	v_lshlrev_b64 v[174:175], 2, v[174:175]
	v_lshl_add_u64 v[176:177], s[16:17], 0, v[174:175]
	v_lshl_add_u64 v[174:175], s[72:73], 0, v[174:175]
	s_waitcnt vmcnt(0)
	v_pk_add_f32 v[46:47], v[26:27], v[46:47]
	v_pk_add_f32 v[44:45], v[24:25], v[44:45]
	global_store_dwordx4 v[146:147], v[44:47], off offset:576
	global_load_dwordx4 v[24:27], v[176:177], off nt
	v_add_u32_e32 v146, 0xb0, v160
	v_ashrrev_i32_e32 v147, 31, v146
	s_waitcnt vmcnt(0)
	v_pk_add_f32 v[34:35], v[34:35], v[26:27]
	v_pk_add_f32 v[32:33], v[32:33], v[24:25]
	global_store_dwordx4 v[174:175], v[32:35], off
	global_load_dwordx4 v[24:27], v[176:177], off offset:64 nt
	s_waitcnt vmcnt(0)
	v_pk_add_f32 v[26:27], v[30:31], v[26:27]
	v_pk_add_f32 v[24:25], v[28:29], v[24:25]
	global_store_dwordx4 v[174:175], v[24:27], off offset:64
	global_load_dwordx4 v[28:31], v[176:177], off offset:512 nt
	s_waitcnt vmcnt(0)
	v_pk_add_f32 v[22:23], v[22:23], v[30:31]
	v_pk_add_f32 v[20:21], v[20:21], v[28:29]
	global_store_dwordx4 v[174:175], v[20:23], off offset:512
	global_load_dwordx4 v[28:31], v[176:177], off offset:576 nt
	v_lshlrev_b64 v[176:177], 11, v[146:147]
	v_lshl_add_u64 v[176:177], v[176:177], 0, v[144:145]
	v_lshlrev_b64 v[176:177], 2, v[176:177]
	v_lshl_add_u64 v[178:179], s[16:17], 0, v[176:177]
	v_lshl_add_u64 v[180:181], s[72:73], 0, v[176:177]
	s_waitcnt vmcnt(0)
	v_pk_add_f32 v[30:31], v[10:11], v[30:31]
	v_pk_add_f32 v[28:29], v[8:9], v[28:29]
	global_store_dwordx4 v[174:175], v[28:31], off offset:576
	global_load_dwordx4 v[8:11], v[178:179], off nt
	s_waitcnt vmcnt(0)
	v_pk_add_f32 v[18:19], v[18:19], v[10:11]
	v_pk_add_f32 v[16:17], v[16:17], v[8:9]
	global_store_dwordx4 v[180:181], v[16:19], off
	global_load_dwordx4 v[8:11], v[178:179], off offset:64 nt
	s_waitcnt vmcnt(0)
	v_pk_add_f32 v[10:11], v[14:15], v[10:11]
	v_pk_add_f32 v[8:9], v[12:13], v[8:9]
	global_store_dwordx4 v[180:181], v[8:11], off offset:64
	global_load_dwordx4 v[12:15], v[178:179], off offset:512 nt
	s_waitcnt vmcnt(0)
	v_pk_add_f32 v[6:7], v[6:7], v[14:15]
	v_pk_add_f32 v[4:5], v[4:5], v[12:13]
	global_store_dwordx4 v[180:181], v[4:7], off offset:512
	global_load_dwordx4 v[174:177], v[178:179], off offset:576 nt
	v_mul_f32_e32 v14, v129, v129
	v_mul_f32_e32 v15, v131, v131
	v_fmac_f32_e32 v14, v128, v128
	v_fmac_f32_e32 v15, v130, v130
	v_add_f32_e32 v14, v14, v15
	v_mul_f32_e32 v15, v121, v121
	v_mul_f32_e32 v178, v123, v123
	v_fmac_f32_e32 v15, v120, v120
	v_fmac_f32_e32 v178, v122, v122
	v_add_f32_e32 v15, v15, v178
	v_add_f32_e32 v14, v14, v15
	v_mul_f32_e32 v15, v117, v117
	v_mul_f32_e32 v178, v119, v119
	v_fmac_f32_e32 v15, v116, v116
	v_fmac_f32_e32 v178, v118, v118
	v_and_b32_e32 v13, 64, v182
	v_add_f32_e32 v15, v15, v178
	v_xor_b32_e32 v12, 16, v182
	v_add_u32_e32 v13, 64, v13
	v_add_f32_e32 v14, v14, v15
	v_mul_f32_e32 v15, v125, v125
	v_mul_f32_e32 v178, v127, v127
	v_cmp_lt_i32_e32 vcc, v12, v13
	v_fmac_f32_e32 v15, v124, v124
	v_fmac_f32_e32 v178, v126, v126
	v_cndmask_b32_e32 v12, v182, v12, vcc
	v_add_f32_e32 v15, v15, v178
	v_lshlrev_b32_e32 v12, 2, v12
	v_add_f32_e32 v14, v14, v15
	ds_bpermute_b32 v15, v12, v14
	v_xor_b32_e32 v178, 32, v182
	v_cmp_lt_i32_e32 vcc, v178, v13
	s_waitcnt lgkmcnt(0)
	v_add_f32_e32 v14, v14, v15
	v_cndmask_b32_e32 v13, v182, v178, vcc
	v_lshlrev_b32_e32 v13, 2, v13
	ds_bpermute_b32 v15, v13, v14
	s_waitcnt vmcnt(0)
	v_pk_add_f32 v[2:3], v[2:3], v[176:177]
	v_pk_add_f32 v[0:1], v[0:1], v[174:175]
	global_store_dwordx4 v[180:181], v[0:3], off offset:576
	s_and_saveexec_b64 s[2:3], s[6:7]
	s_cbranch_execz .LBB0_907
	s_waitcnt lgkmcnt(0)
	v_add_f32_e32 v14, v14, v15
	ds_write_b32 v173, v14

.LBB0_1054:
	s_lshl_b32 s1, s60, 8
	v_add_u32_e32 v158, s1, v161
	v_lshl_add_u32 v156, s0, 8, v163
	v_ashrrev_i32_e32 v159, 31, v158
	v_ashrrev_i32_e32 v157, 31, v156
	v_lshlrev_b64 v[140:141], 13, v[158:159]
	v_lshl_add_u64 v[140:141], s[72:73], 0, v[140:141]
	v_lshlrev_b64 v[184:185], 2, v[156:157]
	v_lshl_add_u64 v[154:155], v[140:141], 0, v[184:185]
	global_load_dwordx4 v[140:143], v[154:155], off nt
	global_load_dwordx4 v[144:147], v[154:155], off offset:64 nt
	global_load_dwordx4 v[148:151], v[154:155], off offset:512 nt
	global_load_dwordx4 v[174:177], v[154:155], off offset:576 nt
	v_or_b32_e32 v152, 16, v158
	v_ashrrev_i32_e32 v153, 31, v152
	v_lshlrev_b64 v[152:153], 13, v[152:153]
	v_lshl_add_u64 v[152:153], s[72:73], 0, v[152:153]
	v_lshl_add_u64 v[152:153], v[152:153], 0, v[184:185]
	s_waitcnt vmcnt(0)
	v_pk_add_f32 v[126:127], v[126:127], v[142:143]
	v_pk_add_f32 v[124:125], v[124:125], v[140:141]
	v_pk_add_f32 v[122:123], v[122:123], v[146:147]
	v_pk_add_f32 v[120:121], v[120:121], v[144:145]
	v_pk_add_f32 v[110:111], v[110:111], v[150:151]
	v_pk_add_f32 v[108:109], v[108:109], v[148:149]
	v_pk_add_f32 v[94:95], v[94:95], v[176:177]
	v_pk_add_f32 v[92:93], v[92:93], v[174:175]
	v_or_b32_e32 v148, 32, v158
	global_load_dwordx4 v[140:143], v[152:153], off nt
	global_load_dwordx4 v[144:147], v[152:153], off offset:64 nt
	global_load_dwordx4 v[174:177], v[152:153], off offset:512 nt
	global_load_dwordx4 v[178:181], v[152:153], off offset:576 nt
	v_ashrrev_i32_e32 v149, 31, v148
	v_lshlrev_b64 v[148:149], 13, v[148:149]
	v_lshl_add_u64 v[148:149], s[72:73], 0, v[148:149]
	v_lshl_add_u64 v[150:151], v[148:149], 0, v[184:185]
	v_or_b32_e32 v148, 48, v158
	v_ashrrev_i32_e32 v149, 31, v148
	v_lshlrev_b64 v[148:149], 13, v[148:149]
	v_lshl_add_u64 v[148:149], s[72:73], 0, v[148:149]
	v_lshl_add_u64 v[148:149], v[148:149], 0, v[184:185]
	v_add_co_u32_e32 v158, vcc, s52, v154
	v_mul_f32_e32 v160, v125, v125
	s_nop 0
	v_addc_co_u32_e32 v159, vcc, 0, v155, vcc
	v_mul_f32_e32 v173, v127, v127
	v_mul_f32_e32 v183, v121, v121
	v_mul_f32_e32 v192, v123, v123
	v_mul_f32_e32 v193, v109, v109
	v_mul_f32_e32 v194, v111, v111
	v_fmac_f32_e32 v160, v124, v124
	v_fmac_f32_e32 v173, v126, v126
	v_fmac_f32_e32 v183, v120, v120
	v_fmac_f32_e32 v192, v122, v122
	v_mul_f32_e32 v195, v93, v93
	v_mul_f32_e32 v196, v95, v95
	v_fmac_f32_e32 v193, v108, v108
	v_fmac_f32_e32 v194, v110, v110
	v_add_f32_e32 v160, v160, v173
	v_add_f32_e32 v173, v183, v192
	v_fmac_f32_e32 v195, v92, v92
	v_fmac_f32_e32 v196, v94, v94
	v_add_f32_e32 v183, v193, v194
	v_add_f32_e32 v160, v160, v173
	v_add_f32_e32 v192, v195, v196
	v_add_f32_e32 v160, v183, v160
	v_add_f32_e32 v160, v192, v160
	v_xor_b32_e32 v183, 32, v182
	s_waitcnt vmcnt(3)
	v_pk_add_f32 v[118:119], v[118:119], v[142:143]
	v_pk_add_f32 v[116:117], v[116:117], v[140:141]
	s_waitcnt vmcnt(2)
	v_pk_add_f32 v[106:107], v[106:107], v[146:147]
	v_pk_add_f32 v[104:105], v[104:105], v[144:145]
	s_waitcnt vmcnt(1)
	v_pk_add_f32 v[90:91], v[90:91], v[176:177]
	v_pk_add_f32 v[88:89], v[88:89], v[174:175]
	s_waitcnt vmcnt(0)
	v_pk_add_f32 v[74:75], v[74:75], v[180:181]
	v_pk_add_f32 v[72:73], v[72:73], v[178:179]
	s_nop 0
	global_load_dwordx4 v[140:143], v[150:151], off nt
	global_load_dwordx4 v[144:147], v[150:151], off offset:64 nt
	global_load_dwordx4 v[174:177], v[150:151], off offset:512 nt
	global_load_dwordx4 v[178:181], v[150:151], off offset:576 nt
	s_waitcnt vmcnt(3)
	v_pk_add_f32 v[114:115], v[114:115], v[142:143]
	v_pk_add_f32 v[112:113], v[112:113], v[140:141]
	s_waitcnt vmcnt(2)
	v_pk_add_f32 v[102:103], v[102:103], v[146:147]
	v_pk_add_f32 v[100:101], v[100:101], v[144:145]
	s_waitcnt vmcnt(1)
	v_pk_add_f32 v[82:83], v[82:83], v[176:177]
	v_pk_add_f32 v[80:81], v[80:81], v[174:175]
	s_waitcnt vmcnt(0)
	v_pk_add_f32 v[66:67], v[66:67], v[180:181]
	v_pk_add_f32 v[64:65], v[64:65], v[178:179]
	s_nop 0
	global_load_dwordx4 v[140:143], v[148:149], off nt
	global_load_dwordx4 v[144:147], v[148:149], off offset:64 nt
	global_load_dwordx4 v[174:177], v[148:149], off offset:512 nt
	global_load_dwordx4 v[178:181], v[148:149], off offset:576 nt
	s_waitcnt vmcnt(3)
	v_pk_add_f32 v[98:99], v[98:99], v[142:143]
	v_pk_add_f32 v[96:97], v[96:97], v[140:141]
	s_waitcnt vmcnt(2)
	v_pk_add_f32 v[78:79], v[78:79], v[146:147]
	v_pk_add_f32 v[76:77], v[76:77], v[144:145]
	s_waitcnt vmcnt(1)
	v_pk_add_f32 v[62:63], v[62:63], v[176:177]
	v_pk_add_f32 v[60:61], v[60:61], v[174:175]
	s_waitcnt vmcnt(0)
	v_pk_add_f32 v[58:59], v[58:59], v[180:181]
	v_pk_add_f32 v[56:57], v[56:57], v[178:179]
	v_lshl_add_u64 v[146:147], v[154:155], 0, s[26:27]
	global_load_dwordx4 v[140:143], v[158:159], off nt
	global_load_dwordx4 v[174:177], v[146:147], off offset:64 nt
	global_load_dwordx4 v[178:181], v[146:147], off offset:512 nt
	global_load_dwordx4 v[184:187], v[146:147], off offset:576 nt
	v_add_co_u32_e32 v144, vcc, s53, v154
	s_waitcnt vmcnt(2)
	v_pk_add_f32 v[70:71], v[70:71], v[176:177]
	v_pk_add_f32 v[86:87], v[86:87], v[142:143]
	v_pk_add_f32 v[84:85], v[84:85], v[140:141]
	v_pk_add_f32 v[68:69], v[68:69], v[174:175]
	s_waitcnt vmcnt(1)
	v_pk_add_f32 v[54:55], v[54:55], v[180:181]
	v_pk_add_f32 v[52:53], v[52:53], v[178:179]
	s_waitcnt vmcnt(0)
	v_pk_add_f32 v[50:51], v[50:51], v[186:187]
	v_pk_add_f32 v[48:49], v[48:49], v[184:185]
	v_addc_co_u32_e32 v145, vcc, 0, v155, vcc
	global_load_dwordx4 v[140:143], v[144:145], off nt
	v_lshl_add_u64 v[144:145], v[154:155], 0, s[28:29]
	global_load_dwordx4 v[174:177], v[144:145], off offset:64 nt
	global_load_dwordx4 v[178:181], v[144:145], off offset:512 nt
	global_load_dwordx4 v[184:187], v[144:145], off offset:576 nt
	v_add_co_u32_e32 v158, vcc, s54, v154
	s_waitcnt vmcnt(2)
	v_pk_add_f32 v[42:43], v[42:43], v[176:177]
	v_pk_add_f32 v[46:47], v[46:47], v[142:143]
	v_pk_add_f32 v[44:45], v[44:45], v[140:141]
	v_pk_add_f32 v[40:41], v[40:41], v[174:175]
	s_waitcnt vmcnt(1)
	v_pk_add_f32 v[38:39], v[38:39], v[180:181]
	v_pk_add_f32 v[36:37], v[36:37], v[178:179]
	s_waitcnt vmcnt(0)
	v_pk_add_f32 v[34:35], v[34:35], v[186:187]
	v_pk_add_f32 v[32:33], v[32:33], v[184:185]
	v_addc_co_u32_e32 v159, vcc, 0, v155, vcc
	v_lshl_add_u64 v[142:143], v[154:155], 0, s[30:31]
	global_load_dwordx4 v[174:177], v[158:159], off nt
	global_load_dwordx4 v[178:181], v[142:143], off offset:64 nt
	global_load_dwordx4 v[184:187], v[142:143], off offset:512 nt
	global_load_dwordx4 v[188:191], v[142:143], off offset:576 nt
	v_add_co_u32_e32 v140, vcc, s55, v154
	v_and_b32_e32 v159, 64, v182
	s_nop 0
	v_addc_co_u32_e32 v141, vcc, 0, v155, vcc
	v_xor_b32_e32 v158, 16, v182
	v_add_u32_e32 v159, 64, v159
	v_cmp_lt_i32_e32 vcc, v158, v159
	s_waitcnt vmcnt(2)
	v_pk_add_f32 v[26:27], v[26:27], v[180:181]
	v_pk_add_f32 v[30:31], v[30:31], v[176:177]
	v_pk_add_f32 v[28:29], v[28:29], v[174:175]
	v_pk_add_f32 v[24:25], v[24:25], v[178:179]
	s_waitcnt vmcnt(1)
	v_pk_add_f32 v[22:23], v[22:23], v[186:187]
	v_pk_add_f32 v[20:21], v[20:21], v[184:185]
	s_waitcnt vmcnt(0)
	v_pk_add_f32 v[18:19], v[18:19], v[190:191]
	v_pk_add_f32 v[16:17], v[16:17], v[188:189]
	v_cndmask_b32_e32 v158, v182, v158, vcc
	global_load_dwordx4 v[174:177], v[140:141], off nt
	v_lshl_add_u64 v[140:141], v[154:155], 0, s[16:17]
	global_load_dwordx4 v[178:181], v[140:141], off offset:64 nt
	global_load_dwordx4 v[184:187], v[140:141], off offset:512 nt
	global_load_dwordx4 v[188:191], v[140:141], off offset:576 nt
	v_lshlrev_b32_e32 v158, 2, v158
	ds_bpermute_b32 v173, v158, v160
	v_cmp_lt_i32_e32 vcc, v183, v159
	s_waitcnt lgkmcnt(0)
	v_add_f32_e32 v160, v160, v173
	v_cndmask_b32_e32 v159, v182, v183, vcc
	v_lshlrev_b32_e32 v159, 2, v159
	ds_bpermute_b32 v173, v159, v160
	s_waitcnt vmcnt(2)
	v_pk_add_f32 v[10:11], v[10:11], v[180:181]
	v_pk_add_f32 v[14:15], v[14:15], v[176:177]
	v_pk_add_f32 v[12:13], v[12:13], v[174:175]
	v_pk_add_f32 v[8:9], v[8:9], v[178:179]
	s_waitcnt vmcnt(1)
	v_pk_add_f32 v[6:7], v[6:7], v[186:187]
	v_pk_add_f32 v[4:5], v[4:5], v[184:185]
	s_waitcnt vmcnt(0)
	v_pk_add_f32 v[2:3], v[2:3], v[190:191]
	v_pk_add_f32 v[0:1], v[0:1], v[188:189]
	s_nop 0
	s_and_saveexec_b64 s[2:3], s[4:5]
	s_cbranch_execz .LBB0_1056
	s_waitcnt lgkmcnt(0)
	v_add_f32_e32 v160, v160, v173
	ds_write_b32 v172, v160

.LBB0_1087:
	v_lshl_add_u64 v[156:157], v[156:157], 2, s[86:87]
	global_load_dwordx4 v[206:209], v[156:157], off nt
	global_load_dwordx4 v[210:213], v[156:157], off offset:64 nt
	global_load_dwordx4 v[214:217], v[156:157], off offset:512 nt
	global_load_dwordx4 v[218:221], v[156:157], off offset:576 nt
	s_waitcnt vmcnt(0)
	s_nop 1
	s_waitcnt lgkmcnt(0)
	v_pk_mul_f32 v[126:127], v[126:127], v[160:161] op_sel_hi:[1,0]
	v_pk_mul_f32 v[124:125], v[124:125], v[160:161] op_sel_hi:[1,0]
	v_pk_mul_f32 v[122:123], v[122:123], v[160:161] op_sel_hi:[1,0]
	v_pk_mul_f32 v[120:121], v[120:121], v[160:161] op_sel_hi:[1,0]
	v_pk_mul_f32 v[110:111], v[110:111], v[160:161] op_sel_hi:[1,0]
	v_pk_mul_f32 v[108:109], v[108:109], v[160:161] op_sel_hi:[1,0]
	v_pk_mul_f32 v[94:95], v[94:95], v[160:161] op_sel_hi:[1,0]
	v_pk_mul_f32 v[92:93], v[92:93], v[160:161] op_sel_hi:[1,0]
	s_andn2_b64 vcc, exec, s[14:15]
	s_waitcnt vmcnt(16)
	v_pk_mul_f32 v[126:127], v[208:209], v[126:127]
	v_pk_mul_f32 v[124:125], v[206:207], v[124:125]
	global_store_dwordx4 v[154:155], v[124:127], off
	s_nop 1
	s_waitcnt vmcnt(16)
	v_pk_mul_f32 v[122:123], v[122:123], v[212:213]
	v_pk_mul_f32 v[120:121], v[120:121], v[210:211]
	global_store_dwordx4 v[154:155], v[120:123], off offset:64
	s_nop 1
	s_waitcnt vmcnt(16)
	v_pk_mul_f32 v[110:111], v[110:111], v[216:217]
	v_pk_mul_f32 v[108:109], v[108:109], v[214:215]
	global_store_dwordx4 v[154:155], v[108:111], off offset:512
	s_nop 1
	v_cndmask_b32_e64 v120, 0, 1, s[14:15]
	v_cmp_ne_u32_e64 s[12:13], 1, v120
	s_waitcnt vmcnt(16)
	v_pk_mul_f32 v[94:95], v[94:95], v[220:221]
	v_pk_mul_f32 v[92:93], v[92:93], v[218:219]
	global_store_dwordx4 v[154:155], v[92:95], off offset:576
	s_cbranch_vccnz .LBB0_1089
	ds_read_b32 v158, v166 offset:64
